# combo2 with P7 select unit loop software-pipelined (next unit's block means + query tiles prefetched one unit ahead) instead of the in-unit hoist
# speedup vs baseline: 1.0032x; 1.0002x over previous
; #define LAS __attribute__((address_space(3)))
; __device__ __forceinline__ void moba_select(const Frame& F, const Args& a) {
;     const f16_t* P = (const f16_t*)(a.ws + WS_P16);
;     const float* kmean = (const float*)(F.ctl + CW_KMEAN);
;     unsigned short* LIST = (unsigned short*)(a.ws + WS_LIST); unsigned short* OFFS = (unsigned short*)(a.ws + WS_OFFS);
;     LAS unsigned char* KMhi = F.lds; LAS unsigned char* KMlo = F.lds + 8192;
;     LAS int* cnt = (LAS int*)(F.lds + 16384);
;     LAS int* off = cnt + 64;
;     LAS int* cur = off + 72;
;     LAS unsigned short* sorted = (LAS unsigned short*)(F.lds + 17408);
;     const int lane = F.lane, fr = lane & 15, G = lane >> 4, w = F.wave, tid = F.tid;
;     for (int unit = F.vcu; unit < BATCH * NBLK * MOBA_H; unit += F.G) {
;         const int h = unit % MOBA_H, qb = (unit / MOBA_H) % NBLK, b = unit / (MOBA_H * NBLK);
;         const size_t ub = (size_t)(b * MOBA_H + h) * NBLK + qb;
;         __syncthreads();
;         if (tid < 64) { cnt[tid] = 0; cur[tid] = 0; }
;         { const int j = tid >> 3, c = tid & 7; const float* src = kmean + ((size_t)(b * MOBA_H + h) * NBLK + j) * HD + 8 * c;
;           const f32x4 x0 = *(const f32x4*)src, x1 = *(const f32x4*)(src + 4);
;     ...
;             const int qi = 16 * (w + 8 * rep) + fr;
;             const f16_t* qp = P + (size_t)(b * SEQ + qb * MOBA_BLK + qi) * NB + h * HD + 8 * G;
;             const h16x8 q0 = *(const h16x8*)qp, q1 = *(const h16x8*)(qp + 32);
.LBB0_863:
	s_cmp_lt_i32 s78, 8
	s_cselect_b64 s[22:23], -1, 0
	s_and_b64 s[0:1], s[22:23], s[0:1]
	s_andn2_b64 vcc, exec, s[0:1]
	s_cbranch_vccnz .LBB0_923
	s_waitcnt vmcnt(0) lgkmcnt(0)
	v_lshrrev_b32_e32 v19, 4, v206
	v_readlane_b32 s0, v238, 2
	s_movk_i32 s38, 0x5ff
	s_cmpk_gt_i32 s0, 0x5ff
	v_bitop3_b32 v41, v19, v0, 7 bitop3:0x78
	v_lshlrev_b32_e32 v40, 2, v19
	s_cbranch_scc1 .LBB0_918
	v_lshrrev_b32_e32 v18, 3, v0
	v_lshlrev_b32_e32 v1, 5, v0
	v_and_b32_e32 v20, 0xe0, v1
	v_xor_b32_e32 v1, v18, v0
	v_lshlrev_b32_e32 v1, 4, v1
	v_and_b32_e32 v7, 0x70, v1
	v_and_b32_e32 v1, 7, v0
	v_mov_b32_e32 v21, 0
	v_bitop3_b32 v9, v19, v1, 4 bitop3:0x36
	v_mbcnt_lo_u32_b32 v1, -1, 0
	v_mbcnt_hi_u32_b32 v5, -1, v1
	v_lshlrev_b32_e32 v26, 1, v0
	v_mov_b32_e32 v27, v21
	v_and_b32_e32 v10, 64, v5
	v_lshl_add_u64 v[2:3], s[76:77], 0, v[26:27]
	s_mov_b64 s[8:9], 0x3700000
	v_add_u32_e32 v11, 64, v10
	v_lshl_add_u64 v[28:29], v[2:3], 0, s[8:9]
	v_xor_b32_e32 v2, 16, v5
	v_cmp_lt_i32_e32 vcc, v2, v11
	s_add_u32 s39, s76, 0x3400000
	s_addc_u32 s40, s77, 0
	v_cndmask_b32_e32 v2, v5, v2, vcc
	v_lshlrev_b32_e32 v27, 2, v2
	v_xor_b32_e32 v2, 32, v5
	v_cmp_lt_i32_e32 vcc, v2, v11
	v_and_b32_e32 v4, 15, v0
	v_readlane_b32 s18, v238, 15
	v_cndmask_b32_e32 v2, v5, v2, vcc
	v_lshlrev_b32_e32 v35, 2, v2
	v_add_u32_e32 v2, -1, v5
	v_cmp_lt_i32_e32 vcc, v2, v10
	v_lshlrev_b32_e32 v8, 7, v4
	s_cmp_lt_u32 s18, 64
	v_cndmask_b32_e32 v2, v2, v5, vcc
	v_lshlrev_b32_e32 v36, 2, v2
	v_add_u32_e32 v2, -2, v5
	v_cmp_lt_i32_e32 vcc, v2, v10
	s_cselect_b64 s[24:25], -1, 0
	s_and_b32 s18, s18, 0xffc0
	v_cndmask_b32_e32 v2, v2, v5, vcc
	v_lshlrev_b32_e32 v37, 2, v2
	v_add_u32_e32 v2, -4, v5
	v_cmp_lt_i32_e32 vcc, v2, v10
	v_lshl_or_b32 v9, v9, 4, v8
	v_lshl_or_b32 v8, v41, 4, v8
	v_cndmask_b32_e32 v2, v2, v5, vcc
	v_lshlrev_b32_e32 v38, 2, v2
	v_add_u32_e32 v2, -8, v5
	v_cmp_lt_i32_e32 vcc, v2, v10
	v_lshl_add_u32 v32, v0, 2, 0
	v_lshl_add_u64 v[22:23], s[6:7], 0, v[20:21]
	v_cndmask_b32_e32 v2, v2, v5, vcc
	v_lshlrev_b32_e32 v39, 2, v2
	v_add_u32_e32 v2, -16, v5
	v_cmp_lt_i32_e32 vcc, v2, v10
	v_lshl_add_u32 v6, v18, 7, 0
	v_lshlrev_b32_e32 v20, 4, v19
	v_cndmask_b32_e32 v2, v2, v5, vcc
	v_lshlrev_b32_e32 v42, 2, v2
	v_subrev_u32_e32 v2, 32, v5
	v_cmp_lt_i32_e32 vcc, v2, v10
	s_movk_i32 s6, 0x41
	v_add_u32_e32 v49, 0, v8
	v_cndmask_b32_e32 v2, v2, v5, vcc
	v_lshlrev_b32_e32 v43, 2, v2
	v_lshlrev_b32_e32 v2, 2, v4
	v_or3_b32 v44, s18, v2, v19
	v_add_u32_e32 v8, 0, v26
	v_lshl_or_b32 v33, s80, 4, v4
	v_lshl_add_u64 v[24:25], s[58:59], 0, v[20:21]
	v_cmp_gt_u32_e64 s[0:1], 16, v206
	v_cmp_eq_u32_e64 s[2:3], 1, v19
	v_lshl_add_u32 v34, v206, 2, 0
	v_cmp_eq_u32_e64 s[4:5], 63, v206
	v_cmp_gt_u32_e64 s[6:7], s6, v0
	v_mov_b32_e32 v1, v21
	v_cmp_eq_u32_e64 s[8:9], 0, v206
	v_cmp_gt_u32_e64 s[10:11], 2, v206
	v_cmp_gt_u32_e64 s[12:13], 4, v206
	v_cmp_gt_u32_e64 s[14:15], 8, v206
	v_cmp_gt_u32_e64 s[16:17], 32, v206
	v_add_u16_e32 v45, 0x200, v44
	v_not_b32_e32 v46, v0
	v_or_b32_e32 v5, 0x600, v0
	v_or_b32_e32 v4, 0x400, v0
	v_or_b32_e32 v3, 0x200, v0
	v_mov_b32_e32 v2, v0
	v_xor_b32_e32 v47, 63, v40
	v_add_u32_e32 v48, 0, v9
	v_add_u32_e32 v50, 0x4400, v8
	s_movk_i32 s41, 0xffc0
	v_add_u32_e32 v51, v6, v7
	s_movk_i32 s42, 0x1400
	v_mov_b32_e32 v52, 1
	s_mov_b64 s[26:27], 0x400
	v_add_u32_e32 v53, 0x4000, v32
	v_mov_b32_e32 v54, 0x88
	v_readlane_b32 s43, v238, 2
	v_lshlrev_b32_e32 v98, 8, v18
	v_mov_b32_e32 v99, 0
	v_lshl_add_u64 v[94:95], v[22:23], 0, v[98:99]
	v_mad_i64_i32 v[96:97], vcc, v33, s42, v[24:25]
	s_mov_b32 s47, s43
	s_mul_hi_u32 s48, s47, 0x2aaaaaab
	s_lshr_b32 s48, s48, 1
	s_mul_i32 s49, s48, 12
	s_sub_i32 s49, s47, s49
	s_lshr_b32 s50, s48, 6
	s_and_b32 s51, s48, 63
	s_mul_i32 s52, s50, 12
	s_add_i32 s52, s52, s49
	s_lshl_b32 s52, s52, 14
	s_mov_b32 s53, 0
	v_lshl_add_u64 v[132:133], s[52:53], 0, v[94:95]
	global_load_dwordx4 v[100:103], v[132:133], off
	global_load_dwordx4 v[104:107], v[132:133], off offset:16
	s_lshl_b32 s54, s50, 14
	s_lshl_b32 s55, s51, 8
	s_add_i32 s54, s54, s55
	s_mul_i32 s54, s54, 0x1400
	s_lshl_b32 s55, s49, 7
	s_add_u32 s54, s54, s55
	s_mov_b32 s55, 0
	v_lshl_add_u64 v[134:135], s[54:55], 0, v[96:97]
	global_load_dwordx4 v[108:111], v[134:135], off
	global_load_dwordx4 v[112:115], v[134:135], off offset:64
	s_add_u32 s54, s54, 0xa0000
	v_lshl_add_u64 v[136:137], s[54:55], 0, v[96:97]
	global_load_dwordx4 v[116:119], v[136:137], off
	global_load_dwordx4 v[120:123], v[136:137], off offset:64
	s_waitcnt vmcnt(0)
	v_mov_b64_e32 v[124:125], v[100:101]
	v_mov_b64_e32 v[126:127], v[102:103]
	v_mov_b64_e32 v[128:129], v[104:105]
	v_mov_b64_e32 v[130:131], v[106:107]
	v_mov_b64_e32 v[240:241], v[108:109]
	v_mov_b64_e32 v[242:243], v[110:111]
	v_mov_b64_e32 v[244:245], v[112:113]
	v_mov_b64_e32 v[246:247], v[114:115]
	v_mov_b64_e32 v[248:249], v[116:117]
	v_mov_b64_e32 v[250:251], v[118:119]
	v_mov_b64_e32 v[252:253], v[120:121]
	v_mov_b64_e32 v[254:255], v[122:123]
	s_add_i32 s47, s43, s88
	s_cmpk_lt_i32 s47, 0x600
	s_cbranch_scc0 .Lp7_pf0_skip
	s_mul_hi_u32 s48, s47, 0x2aaaaaab
	s_lshr_b32 s48, s48, 1
	s_mul_i32 s49, s48, 12
	s_sub_i32 s49, s47, s49
	s_lshr_b32 s50, s48, 6
	s_and_b32 s51, s48, 63
	s_mul_i32 s52, s50, 12
	s_add_i32 s52, s52, s49
	s_lshl_b32 s52, s52, 14
	s_mov_b32 s53, 0
	v_lshl_add_u64 v[132:133], s[52:53], 0, v[94:95]
	global_load_dwordx4 v[100:103], v[132:133], off
	global_load_dwordx4 v[104:107], v[132:133], off offset:16
	s_lshl_b32 s54, s50, 14
	s_lshl_b32 s55, s51, 8
	s_add_i32 s54, s54, s55
	s_mul_i32 s54, s54, 0x1400
	s_lshl_b32 s55, s49, 7
	s_add_u32 s54, s54, s55
	s_mov_b32 s55, 0
	v_lshl_add_u64 v[134:135], s[54:55], 0, v[96:97]
	global_load_dwordx4 v[108:111], v[134:135], off
	global_load_dwordx4 v[112:115], v[134:135], off offset:64
	s_add_u32 s54, s54, 0xa0000
	v_lshl_add_u64 v[136:137], s[54:55], 0, v[96:97]
	global_load_dwordx4 v[116:119], v[136:137], off
	global_load_dwordx4 v[120:123], v[136:137], off offset:64
.Lp7_pf0_skip:
	s_branch .LBB0_867

; #define LAS __attribute__((address_space(3)))
; __device__ __forceinline__ unsigned pkh(float lo, float hi) { f32x2 v = {lo, hi}; h16x2 h = __builtin_convertvector(v, h16x2); return __builtin_bit_cast(unsigned, h); }
; __device__ __forceinline__ void moba_select(const Frame& F, const Args& a) {
;     ...
;         const int h = unit % MOBA_H, qb = (unit / MOBA_H) % NBLK, b = unit / (MOBA_H * NBLK);
;         const size_t ub = (size_t)(b * MOBA_H + h) * NBLK + qb;
;         __syncthreads();
;         if (tid < 64) { cnt[tid] = 0; cur[tid] = 0; }
;         { const int j = tid >> 3, c = tid & 7; const float* src = kmean + ((size_t)(b * MOBA_H + h) * NBLK + j) * HD + 8 * c;
;           const f32x4 x0 = *(const f32x4*)src, x1 = *(const f32x4*)(src + 4);
;           const float v[8] = {x0[0], x0[1], x0[2], x0[3], x1[0], x1[1], x1[2], x1[3]}; float hi[8], lo[8];
; #pragma unroll
;           for (int e = 0; e < 8; ++e) { hi[e] = (float)(_Float16)v[e]; lo[e] = v[e] - hi[e]; }
;           u32x4 wh, wl; wh.x = pkh(hi[0], hi[1]); wh.y = pkh(hi[2], hi[3]); wh.z = pkh(hi[4], hi[5]); wh.w = pkh(hi[6], hi[7]);
;           wl.x = pkh(lo[0], lo[1]); wl.y = pkh(lo[2], lo[3]); wl.z = pkh(lo[4], lo[5]); wl.w = pkh(lo[6], lo[7]);
;           *(LAS u32x4*)(KMhi + j * 128 + ((c ^ (j & 7)) << 4)) = wh; *(LAS u32x4*)(KMlo + j * 128 + ((c ^ (j & 7)) << 4)) = wl; }
;         __syncthreads();
.LBB0_867:
	s_barrier
	s_and_saveexec_b64 s[18:19], s[94:95]
	ds_write2_b32 v53, v21, v21 offset1:136
	s_or_b64 exec, exec, s[18:19]
	s_mul_hi_i32 s18, s43, 0x2aaaaaab
	s_ashr_i32 s19, s18, 1
	s_lshr_b32 s20, s18, 31
	s_add_i32 s19, s19, s20
	s_ashr_i32 s18, s18, 7
	s_mul_i32 s21, s19, 12
	s_add_i32 s20, s18, s20
	s_sub_i32 s21, s43, s21
	s_mul_i32 s18, s20, 12
	s_add_i32 s28, s18, s21
	s_ashr_i32 s29, s28, 31
	s_lshl_b64 s[30:31], s[28:29], 6
	s_ashr_i32 s18, s19, 31
	s_lshr_b32 s18, s18, 26
	s_add_i32 s18, s19, s18
	s_andn2_b32 s18, s18, 63
	s_sub_i32 s29, s19, s18
	s_ashr_i32 s36, s29, 31
	s_cmp_gt_i32 s29, 0
	s_cselect_b64 s[18:19], -1, 0
	s_add_i32 s34, s29, -1
	s_lshl_b32 s35, s20, 14
	s_lshl_b32 s44, s29, 8
	s_lshl_b32 s20, s21, 6
	s_ashr_i32 s37, s34, 4
	s_add_i32 s44, s44, s35
	s_ashr_i32 s21, s20, 31
	s_cmp_gt_i32 s37, -1
	v_lshl_add_u64 v[30:31], s[20:21], 1, v[24:25]
	s_cselect_b64 s[20:21], -1, 0
	s_and_b64 s[18:19], s[18:19], s[20:21]
	v_cndmask_b32_e64 v14, 0, 1, s[18:19]
	v_cmp_ne_u32_e64 s[20:21], 1, v14
	v_mov_b32_e32 v20, 0
	v_mov_b32_e32 v56, 0
	v_add_u32_e32 v55, s44, v33
	s_andn2_b64 vcc, exec, s[18:19]
	v_cvt_f16_f32_e32 v14, v124
	v_cvt_f16_f32_e32 v15, v125
	v_cvt_f16_f32_e32 v16, v126
	v_cvt_f16_f32_e32 v17, v127
	v_cvt_f16_f32_e32 v57, v128
	v_cvt_f16_f32_e32 v58, v129
	v_cvt_f16_f32_e32 v59, v130
	v_cvt_f16_f32_e32 v60, v131
	v_cvt_f32_f16_e32 v14, v14
	v_cvt_f32_f16_e32 v15, v15
	v_cvt_f32_f16_e32 v16, v16
	v_cvt_f32_f16_e32 v17, v17
	v_cvt_f32_f16_e32 v57, v57
	v_cvt_f32_f16_e32 v58, v58
	v_cvt_f32_f16_e32 v59, v59
	v_cvt_f32_f16_e32 v60, v60
	v_sub_f32_e32 v61, v124, v14
	v_sub_f32_e32 v62, v125, v15
	v_sub_f32_e32 v63, v126, v16
	v_sub_f32_e32 v64, v127, v17
	v_sub_f32_e32 v65, v128, v57
	v_sub_f32_e32 v66, v129, v58
	v_sub_f32_e32 v67, v130, v59
	v_sub_f32_e32 v13, v131, v60
	v_cvt_pk_f16_f32 v6, v14, v15
	v_cvt_pk_f16_f32 v7, v16, v17
	v_cvt_pk_f16_f32 v8, v57, v58
	v_cvt_pk_f16_f32 v9, v59, v60
	v_mov_b32_e32 v57, 0
	v_cvt_pk_f16_f32 v10, v61, v62
	v_cvt_pk_f16_f32 v11, v63, v64
	v_cvt_pk_f16_f32 v12, v65, v66
	v_cvt_pk_f16_f32 v13, v67, v13
	ds_write_b128 v51, v[6:9]
	ds_write_b128 v51, v[10:13] offset:8192
	s_waitcnt lgkmcnt(0)
	s_barrier
	s_cbranch_vccnz .LBB0_880
	s_add_i32 s34, s37, 1
	v_mov_b32_e32 v20, 0
	v_mov_b32_e32 v58, v49
	v_mov_b32_e32 v59, v48
	v_mov_b32_e32 v60, v40
	v_mov_b32_e32 v61, v47
	v_mov_b32_e32 v56, 0
	v_mov_b32_e32 v57, 0
	s_branch .LBB0_872

; #define LAS __attribute__((address_space(3)))
; #define SEL_INSERT(k) do { const unsigned a_ = min(t0, (k)); t0 = max(t0, (k)); const unsigned b_ = min(t1, a_); t1 = max(t1, a_); t2 = max(t2, b_); } while (0)
; __device__ __forceinline__ unsigned sel_key(float g, int j) {
;     const unsigned b = __builtin_bit_cast(unsigned, g);
;     const unsigned o = (b & 0x80000000u) ? ~b : (b | 0x80000000u);
;     return (o & ~63u) | (unsigned)(63 - j);
; }
; __device__ __forceinline__ void moba_select(const Frame& F, const Args& a) {
;     ...
;             for (int jt = 0; jt < njt; ++jt) {
;                 f32x4 acc = {0.f, 0.f, 0.f, 0.f};
;                 acc = __builtin_amdgcn_mfma_f32_16x16x32_f16(*(LAS const h16x8*)(KMhi + jt * 2048 + kof0), q0, acc, 0, 0, 0);
;                 acc = __builtin_amdgcn_mfma_f32_16x16x32_f16(*(LAS const h16x8*)(KMhi + jt * 2048 + kof1), q1, acc, 0, 0, 0);
;                 acc = __builtin_amdgcn_mfma_f32_16x16x32_f16(*(LAS const h16x8*)(KMlo + jt * 2048 + kof0), q0, acc, 0, 0, 0);
;                 acc = __builtin_amdgcn_mfma_f32_16x16x32_f16(*(LAS const h16x8*)(KMlo + jt * 2048 + kof1), q1, acc, 0, 0, 0);
; #pragma unroll
;                 for (int e = 0; e < 4; ++e) { const int j = 16 * jt + 4 * G + e; const unsigned k = (j < qb) ? sel_key(acc[e], j) : 0u; SEL_INSERT(k); }
;             }
.LBB0_872:
	ds_read_b128 v[14:17], v58
	ds_read_b128 v[62:65], v58 offset:8192
	ds_read_b128 v[66:69], v59
	ds_read_b128 v[70:73], v59 offset:8192
	v_cmp_gt_i32_e32 vcc, s29, v60
	s_waitcnt lgkmcnt(3)
	v_mfma_f32_16x16x32_f16 v[14:17], v[14:17], v[240:243], 0
	s_waitcnt lgkmcnt(1)
	v_mfma_f32_16x16x32_f16 v[14:17], v[66:69], v[244:247], v[14:17]
	v_mfma_f32_16x16x32_f16 v[14:17], v[62:65], v[240:243], v[14:17]
	v_mov_b32_e32 v62, 0
	s_waitcnt lgkmcnt(0)
	v_mfma_f32_16x16x32_f16 v[14:17], v[70:73], v[244:247], v[14:17]
	s_and_saveexec_b64 s[18:19], vcc
	s_nop 6
	v_not_b32_e32 v62, v14
	v_or_b32_e32 v63, 0x80000000, v14
	v_cmp_gt_i32_e32 vcc, 0, v14
	s_nop 1
	v_cndmask_b32_e32 v14, v63, v62, vcc
	v_and_or_b32 v62, v14, s41, v61
	s_or_b64 exec, exec, s[18:19]
	v_add_u32_e32 v14, 1, v60
	v_cmp_gt_i32_e32 vcc, s29, v14
	v_mov_b32_e32 v14, 0
	v_mov_b32_e32 v63, 0
	s_and_saveexec_b64 s[18:19], vcc
	v_not_b32_e32 v63, v15
	v_or_b32_e32 v64, 0x80000000, v15
	v_cmp_gt_i32_e32 vcc, 0, v15
	s_nop 1
	v_cndmask_b32_e32 v15, v64, v63, vcc
	v_add_u32_e32 v63, -1, v61
	v_and_or_b32 v63, v15, s41, v63
	s_or_b64 exec, exec, s[18:19]
	v_add_u32_e32 v15, 2, v60
	v_cmp_gt_i32_e32 vcc, s29, v15
	s_and_saveexec_b64 s[18:19], vcc
	v_not_b32_e32 v14, v16
	v_or_b32_e32 v15, 0x80000000, v16
	v_cmp_gt_i32_e32 vcc, 0, v16
	s_nop 1
	v_cndmask_b32_e32 v14, v15, v14, vcc
	v_add_u32_e32 v15, -2, v61
	v_and_or_b32 v14, v14, s41, v15
	s_or_b64 exec, exec, s[18:19]
	v_add_u32_e32 v15, 3, v60
	v_cmp_gt_i32_e32 vcc, s29, v15
	v_mov_b32_e32 v15, 0
	s_and_saveexec_b64 s[18:19], vcc
	s_cbranch_execz .LBB0_871
	v_not_b32_e32 v15, v17
	v_or_b32_e32 v16, 0x80000000, v17
	v_cmp_gt_i32_e32 vcc, 0, v17
	s_nop 1
	v_cndmask_b32_e32 v15, v16, v15, vcc
	v_add_u32_e32 v16, -3, v61
	v_and_or_b32 v15, v15, s41, v16
	s_branch .LBB0_871

; #define LAS __attribute__((address_space(3)))
; #define SEL_INSERT(k) do { const unsigned a_ = min(t0, (k)); t0 = max(t0, (k)); const unsigned b_ = min(t1, a_); t1 = max(t1, a_); t2 = max(t2, b_); } while (0)
; __device__ __forceinline__ unsigned sel_key(float g, int j) {
;     const unsigned b = __builtin_bit_cast(unsigned, g);
;     const unsigned o = (b & 0x80000000u) ? ~b : (b | 0x80000000u);
;     return (o & ~63u) | (unsigned)(63 - j);
; }
; __device__ __forceinline__ void moba_select(const Frame& F, const Args& a) {
;     ...
;             for (int jt = 0; jt < njt; ++jt) {
;                 f32x4 acc = {0.f, 0.f, 0.f, 0.f};
;                 acc = __builtin_amdgcn_mfma_f32_16x16x32_f16(*(LAS const h16x8*)(KMhi + jt * 2048 + kof0), q0, acc, 0, 0, 0);
;                 acc = __builtin_amdgcn_mfma_f32_16x16x32_f16(*(LAS const h16x8*)(KMhi + jt * 2048 + kof1), q1, acc, 0, 0, 0);
;                 acc = __builtin_amdgcn_mfma_f32_16x16x32_f16(*(LAS const h16x8*)(KMlo + jt * 2048 + kof0), q0, acc, 0, 0, 0);
;                 acc = __builtin_amdgcn_mfma_f32_16x16x32_f16(*(LAS const h16x8*)(KMlo + jt * 2048 + kof1), q1, acc, 0, 0, 0);
; #pragma unroll
;                 for (int e = 0; e < 4; ++e) { const int j = 16 * jt + 4 * G + e; const unsigned k = (j < qb) ? sel_key(acc[e], j) : 0u; SEL_INSERT(k); }
;             }
.LBB0_885:
	ds_read_b128 v[14:17], v30
	ds_read_b128 v[60:63], v30 offset:8192
	ds_read_b128 v[64:67], v31
	ds_read_b128 v[68:71], v31 offset:8192
	v_cmp_gt_i32_e32 vcc, s29, v55
	s_waitcnt lgkmcnt(3)
	v_mfma_f32_16x16x32_f16 v[14:17], v[14:17], v[248:251], 0
	s_waitcnt lgkmcnt(1)
	v_mfma_f32_16x16x32_f16 v[14:17], v[64:67], v[252:255], v[14:17]
	v_mfma_f32_16x16x32_f16 v[14:17], v[60:63], v[248:251], v[14:17]
	v_mov_b32_e32 v60, 0
	s_waitcnt lgkmcnt(0)
	v_mfma_f32_16x16x32_f16 v[14:17], v[68:71], v[252:255], v[14:17]
	s_and_saveexec_b64 s[20:21], vcc
	s_nop 6
	v_not_b32_e32 v60, v14
	v_or_b32_e32 v61, 0x80000000, v14
	v_cmp_gt_i32_e32 vcc, 0, v14
	s_nop 1
	v_cndmask_b32_e32 v14, v61, v60, vcc
	v_and_or_b32 v60, v14, s41, v59
	s_or_b64 exec, exec, s[20:21]
	v_add_u32_e32 v14, 1, v55
	v_cmp_gt_i32_e32 vcc, s29, v14
	v_mov_b32_e32 v14, 0
	v_mov_b32_e32 v61, 0
	s_and_saveexec_b64 s[20:21], vcc
	v_not_b32_e32 v61, v15
	v_or_b32_e32 v62, 0x80000000, v15
	v_cmp_gt_i32_e32 vcc, 0, v15
	s_nop 1
	v_cndmask_b32_e32 v15, v62, v61, vcc
	v_add_u32_e32 v61, -1, v59
	v_and_or_b32 v61, v15, s41, v61
	s_or_b64 exec, exec, s[20:21]
	v_add_u32_e32 v15, 2, v55
	v_cmp_gt_i32_e32 vcc, s29, v15
	s_and_saveexec_b64 s[20:21], vcc
	v_not_b32_e32 v14, v16
	v_or_b32_e32 v15, 0x80000000, v16
	v_cmp_gt_i32_e32 vcc, 0, v16
	s_nop 1
	v_cndmask_b32_e32 v14, v15, v14, vcc
	v_add_u32_e32 v15, -2, v59
	v_and_or_b32 v14, v14, s41, v15
	s_or_b64 exec, exec, s[20:21]
	v_add_u32_e32 v15, 3, v55
	v_cmp_gt_i32_e32 vcc, s29, v15
	v_mov_b32_e32 v15, 0
	s_and_saveexec_b64 s[20:21], vcc
	s_cbranch_execz .LBB0_884
	v_not_b32_e32 v15, v17
	v_or_b32_e32 v16, 0x80000000, v17
	v_cmp_gt_i32_e32 vcc, 0, v17
	s_nop 1
	v_cndmask_b32_e32 v15, v16, v15, vcc
	v_add_u32_e32 v16, -3, v59
	v_and_or_b32 v15, v15, s41, v16
	s_branch .LBB0_884

; __device__ __forceinline__ void moba_select(const Frame& F, const Args& a) {
;     ...
;         __syncthreads();
;         const int total = off[64];
;         for (int k = tid; k < total; k += 512) LIST[ub * LIST_CAP + k] = sorted[k];
;         if (tid < 65) OFFS[ub * OFFS_LD + tid] = (unsigned short)off[tid];
.LBB0_901:
	s_or_b64 exec, exec, s[20:21]
	s_waitcnt lgkmcnt(0)
	s_barrier
	s_waitcnt vmcnt(0)
	v_mov_b64_e32 v[124:125], v[100:101]
	v_mov_b64_e32 v[126:127], v[102:103]
	v_mov_b64_e32 v[128:129], v[104:105]
	v_mov_b64_e32 v[130:131], v[106:107]
	v_mov_b64_e32 v[240:241], v[108:109]
	v_mov_b64_e32 v[242:243], v[110:111]
	v_mov_b64_e32 v[244:245], v[112:113]
	v_mov_b64_e32 v[246:247], v[114:115]
	v_mov_b64_e32 v[248:249], v[116:117]
	v_mov_b64_e32 v[250:251], v[118:119]
	v_mov_b64_e32 v[252:253], v[120:121]
	v_mov_b64_e32 v[254:255], v[122:123]
	s_lshl_b32 s47, s88, 1
	s_add_i32 s47, s47, s43
	s_cmpk_lt_i32 s47, 0x600
	s_cbranch_scc0 .Lp7_pf1_skip
	s_mul_hi_u32 s48, s47, 0x2aaaaaab
	s_lshr_b32 s48, s48, 1
	s_mul_i32 s49, s48, 12
	s_sub_i32 s49, s47, s49
	s_lshr_b32 s50, s48, 6
	s_and_b32 s51, s48, 63
	s_mul_i32 s52, s50, 12
	s_add_i32 s52, s52, s49
	s_lshl_b32 s52, s52, 14
	s_mov_b32 s53, 0
	v_lshl_add_u64 v[132:133], s[52:53], 0, v[94:95]
	global_load_dwordx4 v[100:103], v[132:133], off
	global_load_dwordx4 v[104:107], v[132:133], off offset:16
	s_lshl_b32 s54, s50, 14
	s_lshl_b32 s55, s51, 8
	s_add_i32 s54, s54, s55
	s_mul_i32 s54, s54, 0x1400
	s_lshl_b32 s55, s49, 7
	s_add_u32 s54, s54, s55
	s_mov_b32 s55, 0
	v_lshl_add_u64 v[134:135], s[54:55], 0, v[96:97]
	global_load_dwordx4 v[108:111], v[134:135], off
	global_load_dwordx4 v[112:115], v[134:135], off offset:64
	s_add_u32 s54, s54, 0xa0000
	v_lshl_add_u64 v[136:137], s[54:55], 0, v[96:97]
	global_load_dwordx4 v[116:119], v[136:137], off
	global_load_dwordx4 v[120:123], v[136:137], off offset:64
.Lp7_pf1_skip:
	ds_read_b32 v10, v21 offset:16896
	s_add_u32 s44, s30, s29
	s_addc_u32 s45, s31, s36
	s_waitcnt lgkmcnt(0)
	v_cmp_lt_i32_e32 vcc, v0, v10
	s_and_saveexec_b64 s[18:19], vcc
	s_cbranch_execz .LBB0_916
	v_add_u32_e32 v9, v10, v46
	v_cmp_lt_u32_e32 vcc, s38, v9
	s_mov_b64 s[30:31], -1
	v_mov_b32_e32 v20, v0
	v_mov_b32_e32 v8, v26
	v_mov_b64_e32 v[6:7], v[0:1]
	s_and_saveexec_b64 s[20:21], vcc
	s_cbranch_execz .LBB0_913
	v_lshrrev_b32_e32 v11, 9, v9
	s_mul_i32 s30, s45, 0x600
	s_mul_hi_u32 s31, s44, 0x600
	v_add_u32_e32 v6, -3, v11
	s_add_i32 s31, s31, s30
	s_mul_i32 s30, s44, 0x600
	v_lshrrev_b32_e32 v7, 2, v6
	s_add_u32 s30, s39, s30
	v_add_u32_e32 v12, 1, v7
	v_cmp_lt_u32_e32 vcc, 11, v6
	v_mov_b64_e32 v[8:9], v[4:5]
	s_addc_u32 s31, s40, s31
	v_mov_b32_e32 v15, 0
	v_mov_b64_e32 v[6:7], v[2:3]
	s_and_saveexec_b64 s[34:35], vcc
	s_cbranch_execz .LBB0_907
	v_mov_b64_e32 v[8:9], v[4:5]
	v_and_b32_e32 v13, 0x7ffffffc, v12
	s_mov_b32 s46, 0
	s_mov_b64 s[36:37], 0
	v_mov_b32_e32 v14, v50
	v_mov_b64_e32 v[6:7], v[2:3]
